# v14 plus the DSA attention loop: K/V tiles HBM->LDS directly, mask word still a register load
# baseline (speedup 1.0000x reference)
; #define LAS __attribute__((address_space(3)))
; __device__ __forceinline__ int fa_ticket(Frame& F, unsigned* head) {
;     LAS int* tk = (LAS int*)(F.lds + fa::OFF_TICKET);
;     if (F.tid == 0) *tk = (int)__hip_atomic_fetch_add(head, 1u, __ATOMIC_RELAXED, __HIP_MEMORY_SCOPE_AGENT);
;     __syncthreads();
;     const int u = *tk;
;     __syncthreads();
;     return u;
; __device__ __forceinline__ void fa_mixer_phase(Frame& F, int l) {
;     ...
;         const int u = fa_ticket(F, F.ctl + CW_QUEUE + 64 * l);
;         if (u >= 512) break;
;         const int qb = 31 - (u >> 4), type = (u >> 2) & 3, h = u & 3, P0 = qb * 256;
;         if (!((FA_MASK >> type) & 1)) continue;
;         fa::UnitArgs U; U.P0 = P0; U.j_lo = 0; U.j_hi = (P0 + 255) / 64 + 1; U.KR = nullptr; U.mk = nullptr; U.gate = nullptr; U.gidx = 0; U.ocmp = nullptr; U.epi = 0; U.old = DM;
.LBB0_4927:
	s_or_b64 exec, exec, s[0:1]
	v_mov_b32_e32 v1, s83
	s_waitcnt vmcnt(0) lgkmcnt(0)
	s_barrier
	ds_read_b32 v1, v1
	s_movk_i32 s0, 0x1ff
	s_waitcnt lgkmcnt(0)
	s_barrier
	v_cmp_lt_i32_e32 vcc, s0, v1
	v_readfirstlane_b32 s2, v1
	s_mov_b64 s[0:1], -1
	s_cbranch_vccnz .LBB0_4922
	s_lshl_b32 s0, s2, 4
	s_and_b32 s12, s0, 0xffffff00
	s_sub_i32 s0, 0x1fc0, s12
	s_lshr_b32 s15, s0, 6
	s_bfe_u32 s10, s2, 0x20002
	s_and_b32 s14, s2, 3
	s_sub_i32 s2, 0x1f00, s12
	s_add_i32 s13, s15, 1
	s_cmp_lt_i32 s10, 2
	s_mov_b64 s[0:1], -1
	s_cbranch_scc1 .LBB0_4968
	s_cmp_gt_i32 s10, 2
	s_cbranch_scc0 .LBB0_4945
; #define LAS __attribute__((address_space(3)))
; __device__ __forceinline__ int v_st(int k, int c) { const int kk = (k & ~0xC) | ((k & 4) << 1) | ((k & 8) >> 1); return ((kk >> 3) * 4 + (c >> 5)) * 512 + ((kk & 7) * 32 + (c & 31)) * 2; }
; __device__ __forceinline__ int v_rd_base(int lane) { return ((lane & 3) << 3) | (((lane >> 2) & 3) << 6) | (((lane >> 4) & 1) << 5) | (((lane >> 5) & 1) << 8); }
; template <int KIND>
; __device__ __forceinline__ void run_unit(LAS char* lds, const UnitArgs& U, int tid_in) {
;     ...
;     const int wid = __builtin_amdgcn_readfirstlane(tid >> 6), lane = tid & 63, r32 = lane & 31, hi = lane >> 5;
;     const int sr = tid >> 4, sc = (tid & 15) * 8;
;     const int qlo = U.P0 + wid * 32, rowpos = qlo + r32;
;     const float sc_ = MLA ? SC192 : SC128; const float C2 = 1.4426950408889634f * sc_;
;     LAS float* wsf = (LAS float*)(lds + OFF_WS) + wid * 96; LAS float* li_l = wsf; LAS float* al_l = wsf + 32; LAS float* g_l = wsf + 64;
;     half8 qr[MLA ? 12 : 8];
;     { const h16* qp = U.Q + (size_t)(wid * 32 + r32) * U.qld + hi * 8;
; #pragma unroll
;       for (int d0 = 0; d0 < (MLA ? 12 : 8); ++d0) qr[d0] = *(const half8*)(qp + d0 * 16); }
;     unsigned mb0 = 0, mb1 = 0, mb2 = 0, mb3 = 0;
;     if constexpr (KIND == K_MOBA) { const int* s = (const int*)U.mk + (size_t)rowpos * 16;
; #pragma unroll
;         for (int i = 0; i < 3; ++i) { const int b = s[i]; if (b >= 0) mb0 |= 1u << b; } }
;     if constexpr (KIND == K_SLC) { const u32x4 m = *(const u32x4*)((const unsigned*)U.mk + (size_t)rowpos * 4); mb0 = m[0]; mb1 = m[1]; mb2 = m[2]; mb3 = m[3]; }
;     const int nvis_row = rowpos >= 31 ? ((rowpos - 31) >> 4) + 1 : 0;
;     const int NT = U.j_hi - U.j_lo;
;     half8 st_k0, st_k1, st_v0, st_v1, st_kr; unsigned dm_lo = 0, dm_hi = 0, dn_lo = 0, dn_hi = 0;
;     const int kws = FA_KSWZ(sr, sc * 2), vst0 = v_st(sr, sc), vst1 = v_st(32 + sr, sc), krw = FA_KRSWZ(tid >> 3, (tid & 7) * 16);
;     const int vb0 = (int)(unsigned)(size_t)(lds + OFF_V) + v_rd_base(lane);
;     ...
;     float m_reg = -1e30f, l_reg = 0.f; f32x16 o[4];
; #pragma unroll
;     for (int d = 0; d < 4; ++d)
; #pragma unroll
;         for (int r = 0; r < 16; ++r) o[d][r] = 0.f;
;     FA_LOADT(U.j_lo); asm volatile("s_waitcnt vmcnt(0)" ::: "memory"); FA_WRITET(0); dm_lo = dn_lo; dm_hi = dn_hi;
	s_lshl_b32 s8, s14, 21
	v_readlane_b32 s0, v253, 60
	s_add_u32 s6, s0, s8
	v_readlane_b32 s0, v253, 61
	s_addc_u32 s7, s0, 0
	s_lshl_b64 s[0:1], s[2:3], 8
	s_add_u32 s0, s6, s0
	s_addc_u32 s1, s7, s1
	v_readlane_b32 s6, v253, 62
	v_mov_b32_e32 v1, v0
	s_add_u32 s6, s6, s8
	v_readlane_b32 s7, v253, 63
	s_addc_u32 s7, s7, 0
	v_ashrrev_i32_e32 v162, 4, v1
	v_readlane_b32 s9, v251, 58
	v_lshlrev_b32_e32 v16, 3, v1
	v_add_u32_e32 v6, 32, v162
	v_ashrrev_i32_e32 v163, 31, v162
	s_add_u32 s8, s9, s8
	v_readlane_b32 s9, v251, 59
	v_and_b32_e32 v2, 0x78, v16
	v_lshlrev_b64 v[8:9], 8, v[162:163]
	v_ashrrev_i32_e32 v7, 31, v6
	s_addc_u32 s9, s9, 0
	v_lshlrev_b32_e32 v4, 1, v2
	v_lshl_add_u64 v[10:11], s[6:7], 0, v[8:9]
	v_mov_b32_e32 v5, v3
	v_lshlrev_b64 v[12:13], 8, v[6:7]
	v_lshl_add_u64 v[10:11], v[10:11], 0, v[4:5]
	v_lshl_add_u64 v[14:15], s[6:7], 0, v[12:13]
	v_lshl_add_u64 v[8:9], s[8:9], 0, v[8:9]
	v_lshl_add_u64 v[14:15], v[14:15], 0, v[4:5]
	global_load_dwordx4 v[114:117], v[10:11], off
	global_load_dwordx4 v[118:121], v[14:15], off
	v_lshl_add_u64 v[8:9], v[8:9], 0, v[4:5]
	v_lshl_add_u64 v[10:11], s[8:9], 0, v[12:13]
	v_lshl_add_u64 v[10:11], v[10:11], 0, v[4:5]
	global_load_dwordx4 v[122:125], v[8:9], off
	global_load_dwordx4 v[126:129], v[10:11], off
	v_readfirstlane_b32 s11, v1
	s_ashr_i32 s16, s11, 6
	v_and_b32_e32 v172, 31, v1
	s_lshl_b32 s11, s16, 5
	v_or_b32_e32 v8, s11, v172
	s_add_i32 s17, s11, s2
	v_ashrrev_i32_e32 v9, 31, v8
	v_bfe_u32 v163, v1, 5, 1
	v_or_b32_e32 v10, s17, v172
	v_lshlrev_b64 v[8:9], 8, v[8:9]
	v_lshlrev_b32_e32 v2, 4, v163
	v_ashrrev_i32_e32 v11, 31, v10
	v_lshl_add_u64 v[8:9], s[0:1], 0, v[8:9]
	v_lshlrev_b64 v[10:11], 10, v[10:11]
	v_lshl_add_u64 v[8:9], v[8:9], 0, v[2:3]
	v_lshl_add_u64 v[12:13], s[84:85], 0, v[10:11]
	global_load_dwordx4 v[130:133], v[8:9], off
	global_load_dwordx4 v[134:137], v[8:9], off offset:32
	global_load_dwordx4 v[138:141], v[8:9], off offset:64
	global_load_dwordx4 v[142:145], v[8:9], off offset:96
	global_load_dwordx2 v[164:165], v[12:13], off
	global_load_dwordx4 v[146:149], v[8:9], off offset:128
	global_load_dwordx4 v[150:153], v[8:9], off offset:160
	global_load_dwordx4 v[154:157], v[8:9], off offset:192
	global_load_dwordx4 v[158:161], v[8:9], off offset:224
	v_and_b32_e32 v7, 0xfffff0, v162
	v_lshlrev_b32_e32 v14, 1, v162
	v_and_or_b32 v7, v14, 8, v7
	v_and_b32_e32 v13, 0xfffff0, v6
	v_lshlrev_b32_e32 v6, 1, v6
	v_lshrrev_b32_e32 v15, 1, v162
	v_bfe_u32 v8, v16, 5, 2
	v_and_b32_e32 v9, 3, v162
	v_lshrrev_b32_e32 v7, 1, v7
	v_and_or_b32 v6, v6, 8, v13
	v_and_or_b32 v9, v15, 4, v9
	v_or_b32_e32 v7, v7, v8
	v_lshrrev_b32_e32 v6, 1, v6
	v_lshlrev_b32_e32 v9, 6, v9
	v_and_b32_e32 v13, 48, v4
	v_lshlrev_b32_e32 v7, 9, v7
	v_or_b32_e32 v6, v6, v8
	v_lshlrev_b32_e32 v12, 8, v162
	v_bitop3_b32 v14, v4, v1, s50 bitop3:0x78
	v_lshlrev_b32_e32 v6, 9, v6
	v_or3_b32 v177, v7, v9, v13
	v_add3_u32 v176, 0, v14, v12
	s_mul_i32 s0, s16, 0x180
	v_or3_b32 v178, v6, v9, v13
	v_add_u32_e32 v6, 0, v177
	s_add_i32 s0, s0, 0
	v_add_u32_e32 v7, 0, v178
	s_waitcnt vmcnt(0)
	v_lshlrev_b32_e32 v175, 4, v1
	v_and_b32_e32 v173, 63, v1
	s_add_i32 s22, s0, 0x14000
	v_lshl_add_u64 v[166:167], s[6:7], 0, v[4:5]
	s_movk_i32 s6, 0x118
	v_bitop3_b32 v181, v2, v175, s50 bitop3:0x78
	v_mov_b32_e32 v17, v3
	v_lshl_add_u64 v[168:169], s[8:9], 0, v[4:5]
	v_and_b32_e32 v98, 15, v0
	v_bfe_u32 v99, v0, 4, 3
	v_xor_b32_e32 v100, v98, v99
	v_sub_u32_e32 v100, v100, v98
	v_lshlrev_b32_e32 v100, 4, v100
	v_ashrrev_i32_e32 v101, 31, v100
	v_lshl_add_u64 v[166:167], v[166:167], 0, v[100:101]
	v_lshrrev_b32_e32 v102, 7, v0
	v_bfe_u32 v103, v0, 2, 3
	v_lshl_or_b32 v102, v102, 3, v103
	v_and_b32_e32 v104, 4, v102
	v_lshlrev_b32_e32 v104, 1, v104
	v_and_b32_e32 v105, 8, v102
	v_lshrrev_b32_e32 v105, 1, v105
	v_and_b32_e32 v102, 0x33, v102
	v_or3_b32 v102, v102, v104, v105
	v_lshrrev_b32_e32 v103, 4, v0
	v_sub_u32_e32 v102, v102, v103
	v_lshlrev_b32_e32 v102, 8, v102
	v_bfe_u32 v103, v0, 5, 2
	v_lshlrev_b32_e32 v103, 6, v103
	v_and_b32_e32 v104, 3, v0
	v_lshl_or_b32 v103, v104, 4, v103
	v_lshlrev_b32_e32 v104, 4, v98
	v_sub_u32_e32 v103, v103, v104
	v_add_u32_e32 v102, v102, v103
	v_ashrrev_i32_e32 v103, 31, v102
	v_lshl_add_u64 v[168:169], v[168:169], 0, v[102:103]
	s_waitcnt vmcnt(12)
	ds_write_b128 v176, v[114:117] offset:32768
	s_waitcnt vmcnt(11)
	ds_write_b128 v176, v[118:121] offset:40960
	s_waitcnt vmcnt(10)
	ds_write_b128 v6, v[122:125]
	s_waitcnt vmcnt(9)
	ds_write_b128 v7, v[126:129]
	v_lshlrev_b32_e32 v6, 1, v1
	v_and_b32_e32 v6, 32, v6
	v_and_b32_e32 v1, 0x70, v175
	v_bitop3_b32 v182, v2, v1, 32 bitop3:0x36
	v_bitop3_b32 v183, v2, v1, 64 bitop3:0x36
	v_bitop3_b32 v184, v2, v1, s77 bitop3:0x36
	v_add_u32_e32 v1, s22, v2
	v_and_or_b32 v2, v16, s6, v6
	v_readlane_b32 s6, v255, 2
	v_and_b32_e32 v7, 0xc0, v175
	v_readlane_b32 s7, v255, 3
	v_mov_b32_e32 v16, v3
	v_add3_u32 v185, v7, 0, v2
	v_lshl_add_u64 v[170:171], s[6:7], 0, v[10:11]
	v_mov_b32_e32 v2, v3
	v_mov_b32_e32 v4, v3
	v_mov_b32_e32 v6, v3
	v_mov_b32_e32 v7, v3
	v_mov_b32_e32 v8, v3
	v_mov_b32_e32 v9, v3
	v_mov_b32_e32 v10, v3
	v_mov_b32_e32 v11, v3
	v_mov_b32_e32 v12, v3
	v_mov_b32_e32 v13, v3
	v_mov_b32_e32 v14, v3
	v_mov_b32_e32 v15, v3
	v_mov_b64_e32 v[32:33], v[16:17]
	v_mov_b64_e32 v[48:49], v[16:17]
	v_mov_b64_e32 v[64:65], v[16:17]
	v_mov_b64_e32 v[80:81], v[16:17]
	s_or_b32 s17, s17, 31
	v_lshl_add_u32 v180, v172, 8, 0
	v_lshlrev_b32_e32 v174, 2, v163
	v_cmp_gt_u32_e64 s[0:1], 32, v173
	v_lshl_add_u32 v179, v172, 2, s22
	s_mov_b32 s22, 0
	v_mov_b32_e32 v187, 0
	v_mov_b32_e32 v186, 0xf149f2ca
	s_movk_i32 s23, 0x4000
	v_mov_b64_e32 v[30:31], v[14:15]
	v_mov_b64_e32 v[28:29], v[12:13]
	v_mov_b64_e32 v[26:27], v[10:11]
	v_mov_b64_e32 v[24:25], v[8:9]
	v_mov_b64_e32 v[22:23], v[6:7]
	v_mov_b64_e32 v[20:21], v[4:5]
	v_mov_b64_e32 v[18:19], v[2:3]
	v_mov_b64_e32 v[46:47], v[14:15]
	v_mov_b64_e32 v[44:45], v[12:13]
	v_mov_b64_e32 v[42:43], v[10:11]
	v_mov_b64_e32 v[40:41], v[8:9]
	v_mov_b64_e32 v[38:39], v[6:7]
	v_mov_b64_e32 v[36:37], v[4:5]
	v_mov_b64_e32 v[34:35], v[2:3]
	v_mov_b64_e32 v[62:63], v[14:15]
	v_mov_b64_e32 v[60:61], v[12:13]
	v_mov_b64_e32 v[58:59], v[10:11]
	v_mov_b64_e32 v[56:57], v[8:9]
	v_mov_b64_e32 v[54:55], v[6:7]
	v_mov_b64_e32 v[52:53], v[4:5]
	v_mov_b64_e32 v[50:51], v[2:3]
	v_mov_b64_e32 v[78:79], v[14:15]
	v_mov_b64_e32 v[76:77], v[12:13]
	v_mov_b64_e32 v[74:75], v[10:11]
	v_mov_b64_e32 v[72:73], v[8:9]
	v_mov_b64_e32 v[70:71], v[6:7]
	v_mov_b64_e32 v[68:69], v[4:5]
	v_mov_b64_e32 v[66:67], v[2:3]
	s_waitcnt vmcnt(4)
	v_mov_b32_e32 v4, v164
	v_mov_b32_e32 v5, v165
	s_mov_b32 s24, 0
	s_waitcnt lgkmcnt(0)
	s_barrier
	s_branch .LBB0_4932

; template <int KIND>
; __device__ __forceinline__ void run_unit(LAS char* lds, const UnitArgs& U, int tid_in) {
;     ...
;         if (t + 1 < NT) FA_LOADT(U.j_lo + t + 1);
.LBB0_4932:
	s_cmp_lt_u32 s24, s15
	s_cselect_b64 s[6:7], -1, 0
	s_cmp_ge_u32 s24, s15
	s_cbranch_scc1 .LBB0_4934
	v_readfirstlane_b32 vcc_hi, v0
	s_and_b32 vcc_lo, s23, 0x4000
	s_lshr_b32 vcc_hi, vcc_hi, 6
	s_lshl_b32 vcc_hi, vcc_hi, 10
	s_add_i32 vcc_lo, vcc_lo, vcc_hi
	v_add_u32_e32 v2, s22, v162
	s_waitcnt vmcnt(0)
	v_add_u32_e32 v4, 64, v2
	v_ashrrev_i32_e32 v5, 31, v4
	v_add_u32_e32 v8, 0x60, v2
	v_lshlrev_b64 v[4:5], 8, v[4:5]
	v_ashrrev_i32_e32 v9, 31, v8
	s_add_i32 m0, vcc_lo, 0x8000
	v_lshl_add_u64 v[6:7], v[166:167], 0, v[4:5]
	v_lshlrev_b64 v[8:9], 8, v[8:9]
	global_load_lds_dwordx4 v[6:7], off
	s_add_i32 m0, vcc_lo, 0xa000
	v_lshl_add_u64 v[10:11], v[166:167], 0, v[8:9]
	v_lshl_add_u64 v[4:5], v[168:169], 0, v[4:5]
	global_load_lds_dwordx4 v[10:11], off
	s_mov_b32 m0, vcc_lo
	v_lshl_add_u64 v[6:7], v[168:169], 0, v[8:9]
	s_nop 0
	global_load_lds_dwordx4 v[4:5], off
	s_add_i32 m0, vcc_lo, 0x2000
	s_nop 0
	global_load_lds_dwordx4 v[6:7], off
	s_nop 0
	global_load_dwordx2 v[4:5], v[170:171], off

; #define FA_WRITET(bf) do { *(LAS half8*)(lds + OFF_K + (bf) * SHM_K + kws) = st_k0; *(LAS half8*)(lds + OFF_K + (bf) * SHM_K + kws + 32 * 256) = st_k1; \
;         *(LAS half8*)(lds + OFF_V + (bf) * SHM_V + vst0) = st_v0; *(LAS half8*)(lds + OFF_V + (bf) * SHM_V + vst1) = st_v1; \
;         if constexpr (MLA) *(LAS half8*)(lds + OFF_KR + (bf) * SHM_KR + krw) = st_kr; } while (0)
; template <int KIND>
; __device__ __forceinline__ void run_unit(LAS char* lds, const UnitArgs& U, int tid_in) {
;     ...
;         if (t + 1 < NT) { asm volatile("s_waitcnt vmcnt(0)" ::: "memory"); FA_WRITET((t + 1) & 1); dm_lo = dn_lo; dm_hi = dn_hi; }
.LBB0_4940:
	s_andn2_b64 vcc, exec, s[6:7]
	s_cbranch_vccnz .LBB0_4931
	s_waitcnt vmcnt(0)
	v_mov_b32_e32 v165, v5
	v_mov_b32_e32 v164, v4
	s_branch .LBB0_4931
